# mixer-A: first key-half row-sum adds moved from the PV2 tail chain into the PV1 MFMA shadow (same add association)
# baseline (speedup 1.0000x reference)
.Lattn_dma_done_a:
	v_exp_f32_e32 v172, v128
	v_exp_f32_e32 v170, v129
	v_exp_f32_e32 v176, v130
	v_exp_f32_e32 v168, v131
	v_exp_f32_e32 v182, v132
	v_exp_f32_e32 v178, v133
	v_exp_f32_e32 v188, v134
	v_exp_f32_e32 v174, v135
	v_exp_f32_e32 v192, v136
	v_exp_f32_e32 v186, v137
	v_exp_f32_e32 v194, v138
	v_exp_f32_e32 v180, v139
	v_exp_f32_e32 v196, v140
	v_exp_f32_e32 v190, v141
	v_exp_f32_e32 v198, v142
	v_exp_f32_e32 v184, v143
	v_cvt_pk_bf16_f32 v144, v173, v169
	v_cvt_pk_bf16_f32 v145, v177, v171
	v_cvt_pk_bf16_f32 v146, v183, v175
	v_cvt_pk_bf16_f32 v147, v189, v179
	v_cvt_pk_bf16_f32 v148, v193, v181
	v_cvt_pk_bf16_f32 v149, v195, v187
	v_cvt_pk_bf16_f32 v150, v197, v185
	v_cvt_pk_bf16_f32 v151, v199, v191
	v_cvt_pk_bf16_f32 v128, v172, v170
	v_cvt_pk_bf16_f32 v129, v176, v168
	v_cvt_pk_bf16_f32 v130, v182, v178
	v_cvt_pk_bf16_f32 v131, v188, v174
	v_cvt_pk_bf16_f32 v132, v192, v186
	v_cvt_pk_bf16_f32 v133, v194, v180
	v_cvt_pk_bf16_f32 v134, v196, v190
	v_cvt_pk_bf16_f32 v135, v198, v184
	v_add3_u32 v160, s7, v162, v160
	v_xad_u32 v252, v163, 64, s7
	v_add_u32_e32 v203, s7, v203
	v_add_u32_e32 v205, s7, v206
	ds_read_b64_tr_b16 v[136:137], v160 offset:32768
	ds_read_b64_tr_b16 v[138:139], v160 offset:34816
	ds_read_b64_tr_b16 v[140:141], v160 offset:36864
	ds_read_b64_tr_b16 v[142:143], v160 offset:38912
	ds_read_b64_tr_b16 v[152:153], v252 offset:32768
	ds_read_b64_tr_b16 v[154:155], v252 offset:34816
	ds_read_b64_tr_b16 v[156:157], v252 offset:36864
	ds_read_b64_tr_b16 v[158:159], v252 offset:38912
	ds_read_b64_tr_b16 v[208:209], v203 offset:32768
	ds_read_b64_tr_b16 v[210:211], v203 offset:34816
	ds_read_b64_tr_b16 v[212:213], v203 offset:36864
	ds_read_b64_tr_b16 v[214:215], v203 offset:38912
	ds_read_b64_tr_b16 v[216:217], v205 offset:32768
	ds_read_b64_tr_b16 v[218:219], v205 offset:34816
	ds_read_b64_tr_b16 v[220:221], v205 offset:36864
	ds_read_b64_tr_b16 v[222:223], v205 offset:38912
	s_waitcnt lgkmcnt(14)
	v_mfma_f32_32x32x16_bf16 v[64:79], v[144:147], v[136:139], v[64:79]
	v_mfma_f32_32x32x16_bf16 v[0:15], v[128:131], v[136:139], v[0:15]
	s_waitcnt lgkmcnt(10)
	v_mfma_f32_32x32x16_bf16 v[80:95], v[144:147], v[152:155], v[80:95]
	v_mfma_f32_32x32x16_bf16 v[16:31], v[128:131], v[152:155], v[16:31]
	s_waitcnt lgkmcnt(6)
	v_mfma_f32_32x32x16_bf16 v[96:111], v[144:147], v[208:211], v[96:111]
	v_mfma_f32_32x32x16_bf16 v[32:47], v[128:131], v[208:211], v[32:47]
	s_waitcnt lgkmcnt(2)
	v_mfma_f32_32x32x16_bf16 v[112:127], v[144:147], v[216:219], v[112:127]
	v_mfma_f32_32x32x16_bf16 v[48:63], v[128:131], v[216:219], v[48:63]
	v_mfma_f32_32x32x16_bf16 v[64:79], v[148:151], v[140:143], v[64:79]
	v_add_f32_e64 v240, v172, v176
	v_add_f32_e64 v241, v173, v177
	v_add_f32_e64 v242, v168, v170
	v_add_f32_e64 v243, v169, v171
	v_mfma_f32_32x32x16_bf16 v[0:15], v[132:135], v[140:143], v[0:15]
	v_pk_add_f32 v[244:245], v[182:183], v[188:189]
	v_pk_add_f32 v[240:241], v[244:245], v[240:241]
	v_pk_add_f32 v[244:245], v[174:175], v[178:179]
	v_mfma_f32_32x32x16_bf16 v[80:95], v[148:151], v[156:159], v[80:95]
	v_pk_add_f32 v[242:243], v[244:245], v[242:243]
	v_pk_add_f32 v[244:245], v[192:193], v[194:195]
	v_add_f32_e64 v240, v244, v240
	v_add_f32_e64 v241, v245, v241
	v_mfma_f32_32x32x16_bf16 v[16:31], v[132:135], v[156:159], v[16:31]
	v_add_f32_e64 v244, v180, v186
	v_add_f32_e64 v245, v181, v187
	v_add_f32_e64 v242, v244, v242
	v_add_f32_e64 v243, v245, v243
	v_mfma_f32_32x32x16_bf16 v[96:111], v[148:151], v[212:215], v[96:111]
	v_pk_add_f32 v[244:245], v[196:197], v[198:199]
	v_pk_add_f32 v[240:241], v[244:245], v[240:241]
	v_pk_add_f32 v[244:245], v[184:185], v[190:191]
	v_mfma_f32_32x32x16_bf16 v[32:47], v[132:135], v[212:215], v[32:47]
	v_add_f32_e64 v242, v244, v242
	v_add_f32_e64 v243, v245, v243
	v_add_f32_e64 v240, v240, v242
	v_add_f32_e64 v241, v241, v243
	s_waitcnt lgkmcnt(0)
	v_mfma_f32_32x32x16_bf16 v[112:127], v[148:151], v[220:223], v[112:127]
	v_pk_add_f32 v[166:167], v[166:167], v[240:241]
	v_mfma_f32_32x32x16_bf16 v[48:63], v[132:135], v[220:223], v[48:63]
	ds_read_b128 v[128:131], v207 offset:4096
	ds_read_b128 v[132:135], v224
	ds_read_b128 v[136:139], v225 offset:4096
	ds_read_b128 v[140:143], v226
	s_waitcnt lgkmcnt(2)
	v_mfma_f32_32x32x16_bf16 v[144:159], v[128:131], v[132:135], 0
	ds_read_b128 v[128:131], v227 offset:4096
	ds_read_b128 v[132:135], v228
	s_waitcnt lgkmcnt(2)
	v_mfma_f32_32x32x16_bf16 v[144:159], v[136:139], v[140:143], v[144:159]
	ds_read_b128 v[136:139], v230 offset:4096
	ds_read_b128 v[140:143], v232
	s_waitcnt lgkmcnt(2)
	v_mfma_f32_32x32x16_bf16 v[144:159], v[128:131], v[132:135], v[144:159]
	ds_read_b128 v[128:131], v207 offset:12288
	ds_read_b128 v[132:135], v224 offset:4096
	s_waitcnt lgkmcnt(2)
	v_mfma_f32_32x32x16_bf16 v[144:159], v[136:139], v[140:143], v[144:159]
	ds_read_b128 v[208:211], v225 offset:12288
	ds_read_b128 v[212:215], v226 offset:4096
	s_waitcnt lgkmcnt(2)
	v_mfma_f32_32x32x16_bf16 v[128:143], v[128:131], v[132:135], 0
	s_nop 7
	v_exp_f32_e32 v229, v144
	v_exp_f32_e32 v145, v145
	v_exp_f32_e32 v231, v146
	v_exp_f32_e32 v147, v147
	ds_read_b128 v[216:219], v227 offset:12288
	ds_read_b128 v[220:223], v228 offset:4096
	s_waitcnt lgkmcnt(2)
	v_mfma_f32_32x32x16_bf16 v[128:143], v[208:211], v[212:215], v[128:143]
	v_exp_f32_e32 v233, v148
	v_exp_f32_e32 v235, v149
	v_exp_f32_e32 v237, v150
	v_exp_f32_e32 v239, v151
	ds_read_b128 v[148:151], v230 offset:12288
	ds_read_b128 v[208:211], v232 offset:4096
	s_waitcnt lgkmcnt(2)
	v_mfma_f32_32x32x16_bf16 v[128:143], v[216:219], v[220:223], v[128:143]
	v_exp_f32_e32 v241, v152
	v_exp_f32_e32 v243, v153
	v_exp_f32_e32 v245, v154
	v_exp_f32_e32 v247, v155
	s_waitcnt lgkmcnt(0)
	v_mfma_f32_32x32x16_bf16 v[128:143], v[148:151], v[208:211], v[128:143]
	v_exp_f32_e32 v249, v156
	v_exp_f32_e32 v251, v157
	v_exp_f32_e32 v207, v158
	v_exp_f32_e32 v163, v159
	s_nop 7
	v_exp_f32_e32 v228, v128
	v_exp_f32_e32 v146, v129
	v_exp_f32_e32 v230, v130
	v_exp_f32_e32 v144, v131
	v_exp_f32_e32 v232, v132
	v_exp_f32_e32 v238, v133
	v_exp_f32_e32 v236, v134
	v_exp_f32_e32 v234, v135
	v_exp_f32_e32 v240, v136
	v_exp_f32_e32 v246, v137
	v_exp_f32_e32 v244, v138
	v_exp_f32_e32 v242, v139
	v_exp_f32_e32 v248, v140
	v_exp_f32_e32 v162, v141
	v_exp_f32_e32 v206, v142
	v_exp_f32_e32 v250, v143
	v_cvt_pk_bf16_f32 v148, v229, v145
	v_cvt_pk_bf16_f32 v149, v231, v147
	v_cvt_pk_bf16_f32 v150, v233, v235
	v_cvt_pk_bf16_f32 v151, v237, v239
	v_cvt_pk_bf16_f32 v152, v241, v243
	v_cvt_pk_bf16_f32 v153, v245, v247
	v_cvt_pk_bf16_f32 v154, v249, v251
	v_cvt_pk_bf16_f32 v155, v207, v163
	v_cvt_pk_bf16_f32 v128, v228, v146
	v_cvt_pk_bf16_f32 v129, v230, v144
	v_cvt_pk_bf16_f32 v130, v232, v238
	v_cvt_pk_bf16_f32 v131, v236, v234
	v_cvt_pk_bf16_f32 v132, v240, v246
	v_cvt_pk_bf16_f32 v133, v244, v242
	v_cvt_pk_bf16_f32 v134, v248, v162
	v_cvt_pk_bf16_f32 v135, v206, v250
	s_addk_i32 s5, 0x4000
	s_add_i32 s4, s4, 0x10000
	s_and_b32 s7, s5, 0x4000
	ds_read_b64_tr_b16 v[136:137], v160 offset:40960
	ds_read_b64_tr_b16 v[138:139], v160 offset:43008
	ds_read_b64_tr_b16 v[140:141], v160 offset:45056
	ds_read_b64_tr_b16 v[142:143], v160 offset:47104
	ds_read_b64_tr_b16 v[156:157], v252 offset:40960
	ds_read_b64_tr_b16 v[158:159], v252 offset:43008
	ds_read_b64_tr_b16 v[208:209], v252 offset:45056
	ds_read_b64_tr_b16 v[210:211], v252 offset:47104
	ds_read_b64_tr_b16 v[212:213], v203 offset:40960
	ds_read_b64_tr_b16 v[214:215], v203 offset:43008
	ds_read_b64_tr_b16 v[216:217], v203 offset:45056
	ds_read_b64_tr_b16 v[218:219], v203 offset:47104
	ds_read_b64_tr_b16 v[220:221], v205 offset:40960
	ds_read_b64_tr_b16 v[222:223], v205 offset:43008
	ds_read_b64_tr_b16 v[224:225], v205 offset:45056
	ds_read_b64_tr_b16 v[226:227], v205 offset:47104
	s_waitcnt lgkmcnt(14)
	v_mfma_f32_32x32x16_bf16 v[64:79], v[148:151], v[136:139], v[64:79]
	v_mfma_f32_32x32x16_bf16 v[0:15], v[128:131], v[136:139], v[0:15]
	s_waitcnt lgkmcnt(10)
	v_mfma_f32_32x32x16_bf16 v[80:95], v[148:151], v[156:159], v[80:95]
	v_mfma_f32_32x32x16_bf16 v[16:31], v[128:131], v[156:159], v[16:31]
	s_waitcnt lgkmcnt(6)
	v_mfma_f32_32x32x16_bf16 v[96:111], v[148:151], v[212:215], v[96:111]
	v_mfma_f32_32x32x16_bf16 v[32:47], v[128:131], v[212:215], v[32:47]
	s_waitcnt lgkmcnt(2)
	v_mfma_f32_32x32x16_bf16 v[112:127], v[148:151], v[220:223], v[112:127]
	v_mfma_f32_32x32x16_bf16 v[48:63], v[128:131], v[220:223], v[48:63]
	v_pk_add_f32 v[138:139], v[232:233], v[236:237]
	v_mfma_f32_32x32x16_bf16 v[64:79], v[152:155], v[140:143], v[64:79]
	v_add_f32_e64 v136, v144, v146
	v_add_f32_e64 v137, v145, v147
	v_mfma_f32_32x32x16_bf16 v[0:15], v[132:135], v[140:143], v[0:15]
	v_pk_add_f32 v[130:131], v[228:229], v[230:231]
	v_mfma_f32_32x32x16_bf16 v[80:95], v[152:155], v[208:211], v[80:95]
	v_add_f32_e64 v130, v138, v130
	v_add_f32_e64 v131, v139, v131
	v_add_f32_e64 v138, v234, v238
	v_add_f32_e64 v139, v235, v239
	v_add_f32_e64 v136, v138, v136
	v_add_f32_e64 v137, v139, v137
	v_pk_add_f32 v[138:139], v[240:241], v[244:245]
	s_nop 0
	v_pk_add_f32 v[130:131], v[138:139], v[130:131]
	v_mfma_f32_32x32x16_bf16 v[16:31], v[132:135], v[208:211], v[16:31]
	v_add_f32_e64 v138, v242, v246
	v_add_f32_e64 v139, v243, v247
	v_add_f32_e64 v136, v138, v136
	v_add_f32_e64 v137, v139, v137
	v_add_f32_e64 v138, v248, v206
	v_add_f32_e64 v139, v249, v207
	v_pk_add_f32 v[130:131], v[138:139], v[130:131]
	v_pk_add_f32 v[138:139], v[250:251], v[162:163]
	v_mfma_f32_32x32x16_bf16 v[96:111], v[152:155], v[216:219], v[96:111]
	v_add_f32_e64 v136, v138, v136
	v_add_f32_e64 v137, v139, v137
	v_add_f32_e64 v130, v130, v136
	v_add_f32_e64 v131, v131, v137
	v_add_f32_e64 v166, v166, v130
	v_add_f32_e64 v167, v167, v131
	v_mfma_f32_32x32x16_bf16 v[32:47], v[132:135], v[216:219], v[32:47]
	s_waitcnt lgkmcnt(0)
	v_mfma_f32_32x32x16_bf16 v[112:127], v[152:155], v[224:227], v[112:127]
	v_mfma_f32_32x32x16_bf16 v[48:63], v[132:135], v[224:227], v[48:63]
	s_waitcnt vmcnt(0)
	s_cmp_eq_u32 s4, 0x400000
	s_cbranch_scc0 .Lattn_head_a
	s_barrier
